# speedup vs baseline: 1.0034x; 1.0021x over previous
; template <int NT, int BM, int BN, bool PLAIN, int NSTAGE, bool EPI_LDS>
; __device__ __forceinline__ void gemm_tile(const Params& p, const GemmDesc& g, bf16_t* lds, const int tid) {
;     ...
;   const int r0 = tid >> 3, c0 = tid & 7;
;   unsigned aoff[PLAIN ? 1 : NA];
;   const char* abase = (const char*)g.A;
;   if (PLAIN) {
;     abase = (const char*)(g.A + (long)m0 * g.lda_lo);
;     aoff[0] = (unsigned)((r0 * (int)g.lda_lo + c0 * 8) * 2);
;   } else {
; #pragma unroll
;     for (int i = 0; i < NA; ++i) {
;       int ra = m0 + r0 + RP * i;
;       int rlo = ra & g.rmask; rlo = rlo < g.rclamp ? rlo : g.rclamp;
;       aoff[i] = (unsigned)(((long)rlo * g.lda_lo + (long)(ra >> g.rshift) * g.lda_hi + c0 * 8) * 2);
;     }
;   }
;   const char* bbase = (const char*)(g.Bt + (long)n0 * g.ldb);
;   const unsigned boff = (unsigned)((r0 * (int)g.ldb + c0 * 8) * 2);
;   const long astepP = (long)RP * g.lda_lo * 2, bstepP = (long)RP * g.ldb * 2;
;   u32x4 ra4[NA], rb4[NB];
;   f32x4 acc[MI][NI];
; #pragma unroll
;   for (int i = 0; i < MI; ++i)
; #pragma unroll
;     for (int j = 0; j < NI; ++j) acc[i][j] = f32x4{0.f, 0.f, 0.f, 0.f};
;   const int nk = g.K >> 6;
;     ...
;   constexpr int STAGE_BYTES = (BM + BN) * 128;
;   char* const ldsb = (char*)lds;
;   const unsigned woff = (unsigned)(((r0 >> 4) * 2 + (c0 >> 2)) * 1024 + (((((r0 & 15) ^ (c0 >> 2)) * 64) + (c0 & 3) * 16) ^ (((r0 & 15) >> 3) << 5)));
;   const unsigned roff = (unsigned)(((fr * 64) + fq * 16) ^ ((fr >> 3) << 5));
;   const int roff1d = (int)((((fr ^ 1) * 64 + fq * 16) ^ ((fr >> 3) << 5))) - (int)roff;
;     ...
;     GLOAD(0)
;     __syncthreads();
;     LWRITE(0)
;     if (nk > 1) GLOAD(1)
;     __syncthreads();
.LBB0_896:
	v_lshrrev_b32_e32 v0, 6, v224
	v_and_b32_e32 v2, 63, v224
	v_readfirstlane_b32 s57, v0
	v_lshrrev_b32_e32 v3, 3, v2
	v_bfe_u32 v4, v2, 4, 2
	v_and_b32_e32 v5, 3, v2
	v_xor_b32_e32 v4, v4, v5
	v_lshlrev_b32_e32 v4, 4, v4
	v_bfe_u32 v5, v2, 2, 1
	v_lshl_or_b32 v4, v5, 6, v4
	v_xor_b32_e32 v5, 64, v4
	s_cmp_ge_u32 s57, 4
	s_cselect_b32 s58, s26, s52
	s_cselect_b32 s59, s41, s42
	s_cselect_b32 s60, s28, s30
	s_cselect_b32 s61, s29, s31
	s_and_b32 s62, s57, 3
	s_lshl_b32 s62, s62, 6
	s_add_i32 s59, s59, s62
	s_mul_i32 s59, s59, s58
	s_lshl_b32 s58, s58, 1
	s_lshl_b32 s59, s59, 1
	s_add_u32 s60, s60, s59
	s_addc_u32 s61, s61, 0
	v_mul_lo_u32 v3, v3, s58
	s_lshl_b32 s62, s58, 3
	v_add_u32_e32 v162, v3, v4
	v_add3_u32 v163, v3, v5, s62
	s_lshl_b32 s62, s58, 4
	v_add_u32_e32 v164, s62, v162
	v_add_u32_e32 v165, s62, v163
	v_add_u32_e32 v166, s62, v164
	v_add_u32_e32 v167, s62, v165
	v_add_u32_e32 v168, s62, v166
	v_add_u32_e32 v169, s62, v167
	s_lshl_b32 s57, s57, 13
	s_barrier
	s_mov_b32 m0, s57
	s_nop 0
	global_load_lds_dwordx4 v162, s[60:61]
	s_add_u32 m0, m0, 0x400
	s_nop 0
	global_load_lds_dwordx4 v163, s[60:61]
	s_add_u32 m0, m0, 0x400
	s_nop 0
	global_load_lds_dwordx4 v164, s[60:61]
	s_add_u32 m0, m0, 0x400
	s_nop 0
	global_load_lds_dwordx4 v165, s[60:61]
	s_add_u32 m0, m0, 0x400
	s_nop 0
	global_load_lds_dwordx4 v166, s[60:61]
	s_add_u32 m0, m0, 0x400
	s_nop 0
	global_load_lds_dwordx4 v167, s[60:61]
	s_add_u32 m0, m0, 0x400
	s_nop 0
	global_load_lds_dwordx4 v168, s[60:61]
	s_add_u32 m0, m0, 0x400
	s_nop 0
	global_load_lds_dwordx4 v169, s[60:61]
	s_add_u32 s60, s60, 0x80
	s_addc_u32 s61, s61, 0
	s_add_u32 m0, s57, 0x10000
	s_nop 0
	global_load_lds_dwordx4 v162, s[60:61]
	s_add_u32 m0, m0, 0x400
	s_nop 0
	global_load_lds_dwordx4 v163, s[60:61]
	s_add_u32 m0, m0, 0x400
	s_nop 0
	global_load_lds_dwordx4 v164, s[60:61]
	s_add_u32 m0, m0, 0x400
	s_nop 0
	global_load_lds_dwordx4 v165, s[60:61]
	v_mov_b32_e32 v110, 0
	v_mov_b32_e32 v111, v110
	v_mov_b32_e32 v112, v110
	v_mov_b32_e32 v113, v110
	v_mov_b32_e32 v90, v110
	v_mov_b32_e32 v91, v110
	v_mov_b32_e32 v92, v110
	v_mov_b32_e32 v93, v110
	v_mov_b32_e32 v40, v110
	v_mov_b32_e32 v41, v110
	v_mov_b32_e32 v42, v110
	v_mov_b32_e32 v43, v110
	v_mov_b32_e32 v44, v110
	v_mov_b32_e32 v45, v110
	v_mov_b32_e32 v46, v110
	v_mov_b32_e32 v47, v110
	v_mov_b32_e32 v48, v110
	v_mov_b32_e32 v49, v110
	v_mov_b32_e32 v50, v110
	v_mov_b32_e32 v51, v110
	v_mov_b32_e32 v52, v110
	v_mov_b32_e32 v53, v110
	v_mov_b32_e32 v54, v110
	v_mov_b32_e32 v55, v110
	v_mov_b32_e32 v56, v110
	v_mov_b32_e32 v57, v110
	v_mov_b32_e32 v58, v110
	v_mov_b32_e32 v59, v110
	v_mov_b32_e32 v60, v110
	v_mov_b32_e32 v61, v110
	v_mov_b32_e32 v62, v110
	v_mov_b32_e32 v63, v110
	v_mov_b32_e32 v64, v110
	v_mov_b32_e32 v65, v110
	v_mov_b32_e32 v66, v110
	v_mov_b32_e32 v67, v110
	v_mov_b32_e32 v68, v110
	v_mov_b32_e32 v69, v110
	v_mov_b32_e32 v70, v110
	v_mov_b32_e32 v71, v110
	v_mov_b32_e32 v72, v110
	v_mov_b32_e32 v73, v110
	v_mov_b32_e32 v74, v110
	v_mov_b32_e32 v75, v110
	v_mov_b32_e32 v76, v110
	v_mov_b32_e32 v34, v110
	v_mov_b32_e32 v35, v110
	v_mov_b32_e32 v36, v110
	v_mov_b32_e32 v37, v110
	v_mov_b32_e32 v38, v110
	v_mov_b32_e32 v39, v110
	v_mov_b32_e32 v77, v110
	v_mov_b32_e32 v78, v110
	v_mov_b32_e32 v79, v110
	v_mov_b32_e32 v80, v110
	v_mov_b32_e32 v81, v110
	v_mov_b32_e32 v82, v110
	v_mov_b32_e32 v83, v110
	v_mov_b32_e32 v84, v110
	v_mov_b32_e32 v85, v110
	v_mov_b32_e32 v86, v110
	v_mov_b32_e32 v87, v110
	v_mov_b32_e32 v88, v110
	v_mov_b32_e32 v89, v110
	v_mov_b32_e32 v94, v110
	v_mov_b32_e32 v95, v110
	v_mov_b32_e32 v96, v110
	v_mov_b32_e32 v97, v110
	v_mov_b32_e32 v98, v110
	v_mov_b32_e32 v99, v110
	v_mov_b32_e32 v100, v110
	v_mov_b32_e32 v101, v110
	v_mov_b32_e32 v102, v110
	v_mov_b32_e32 v103, v110
	v_mov_b32_e32 v104, v110
	v_mov_b32_e32 v105, v110
	v_mov_b32_e32 v106, v110
	v_mov_b32_e32 v107, v110
	v_mov_b32_e32 v108, v110
	v_mov_b32_e32 v109, v110
	v_mov_b32_e32 v114, v110
	v_mov_b32_e32 v115, v110
	v_mov_b32_e32 v116, v110
	v_mov_b32_e32 v117, v110
	v_mov_b32_e32 v118, v110
	v_mov_b32_e32 v119, v110
	v_mov_b32_e32 v120, v110
	v_mov_b32_e32 v121, v110
	v_mov_b32_e32 v122, v110
	v_mov_b32_e32 v123, v110
	v_mov_b32_e32 v124, v110
	v_mov_b32_e32 v125, v110
	v_mov_b32_e32 v126, v110
	v_mov_b32_e32 v127, v110
	v_mov_b32_e32 v128, v110
	v_mov_b32_e32 v129, v110
	v_mov_b32_e32 v130, v110
	v_mov_b32_e32 v131, v110
	v_mov_b32_e32 v132, v110
	v_mov_b32_e32 v133, v110
	v_mov_b32_e32 v134, v110
	v_mov_b32_e32 v135, v110
	v_mov_b32_e32 v136, v110
	v_mov_b32_e32 v137, v110
	v_mov_b32_e32 v138, v110
	v_mov_b32_e32 v139, v110
	v_mov_b32_e32 v140, v110
	v_mov_b32_e32 v141, v110
	v_mov_b32_e32 v142, v110
	v_mov_b32_e32 v143, v110
	v_mov_b32_e32 v144, v110
	v_mov_b32_e32 v145, v110
	v_mov_b32_e32 v146, v110
	v_mov_b32_e32 v147, v110
	v_mov_b32_e32 v148, v110
	v_mov_b32_e32 v149, v110
	v_mov_b32_e32 v150, v110
	v_mov_b32_e32 v151, v110
	v_mov_b32_e32 v152, v110
	v_mov_b32_e32 v153, v110
	v_mov_b32_e32 v154, v110
	v_mov_b32_e32 v155, v110
	v_mov_b32_e32 v156, v110
	v_mov_b32_e32 v157, v110
	v_mov_b32_e32 v158, v110
	v_mov_b32_e32 v159, v110
	v_mov_b32_e32 v160, v110
	v_mov_b32_e32 v161, v110
	s_add_i32 s3, s23, -2
	s_mov_b32 s26, 0
	s_mov_b32 s27, s3
	s_waitcnt vmcnt(4)
	s_barrier
	v_add_u32_e32 v19, v180, v184
	v_add_u32_e32 v18, v180, v183
	ds_read_b128 v[2:5], v19 offset:32768
	ds_read_b128 v[6:9], v19 offset:34816
	ds_read_b128 v[10:13], v19 offset:36864
	ds_read_b128 v[14:17], v19 offset:38912
	ds_read_b128 v[202:205], v18
	ds_read_b128 v[206:209], v18 offset:2048
	ds_read_b128 v[226:229], v18 offset:4096
	.p2align 6
